# v26: v22 + grid-barrier group id = blockIdx & 7 (XCC_ID reads 0 on this GPU, so the hierarchical barrier was running flat: one 256-way counter); now 8 groups of 32
# speedup vs baseline: 1.0027x; 1.0027x over previous
; #define LAS __attribute__((address_space(3)))
; __device__ __forceinline__ unsigned xb_add(unsigned* p, unsigned v) { return __hip_atomic_fetch_add(p, v, __ATOMIC_RELAXED, __HIP_MEMORY_SCOPE_AGENT); }
; __device__ __forceinline__ unsigned xb_xcc_id() { return (unsigned)__builtin_amdgcn_s_getreg((3 << 11) | 20) & 0xFu; }
; __device__ __forceinline__ XcdBarrier xcd_barrier_post(unsigned* bar, volatile LAS unsigned* st) {
;     XcdBarrier b; b.bar = bar; b.x = xb_xcc_id(); b.st = st;
;     if (threadIdx.x == 0) (void)xb_add(&bar[XB_XCNT(b.x)], 1u);
;     return b;
; __global__ void __launch_bounds__(NWAVES * 64, 2) fwd_megakernel(Args args) {
;     ...
;     volatile LAS unsigned* bar_st = (volatile LAS unsigned*)(lds + RING_BYTES + 32);
;     unsigned* bar_words = (unsigned*)ws;
;     if (threadIdx.x < 2) bar_st[threadIdx.x] = 0u;
;     __syncthreads();
;     const XcdBarrier xbar = xcd_barrier_post(bar_words, bar_st);
_Z14fwd_megakernel4Args:
	s_load_dwordx16 s[48:63], s[0:1], 0x80
	s_load_dword s93, s[0:1], 0xc0
	s_mov_b32 s94, s2
	s_add_u32 s2, s0, 0xc0
	s_addc_u32 s3, s1, 0
	v_cmp_gt_u32_e32 vcc, 2, v0
	v_writelane_b32 v254, s2, 0
	s_nop 1
	v_writelane_b32 v254, s3, 1
	s_and_saveexec_b64 s[4:5], vcc
	v_lshl_add_u32 v1, v0, 2, 0
	v_add_u32_e32 v1, 0x20020, v1
	v_mov_b32_e32 v2, 0
	ds_write_b32 v1, v2
	s_or_b64 exec, exec, s[4:5]
	s_waitcnt lgkmcnt(0)
	s_barrier
	s_getreg_b32 s2, hwreg(HW_REG_XCC_ID, 0, 4)
	s_and_b32 s33, s94, 7
	v_cmp_ne_u32_e64 s[4:5], 0, v0
	v_cmp_eq_u32_e64 s[2:3], 0, v0
	s_mov_b64 s[6:7], exec
	s_nop 0
	v_writelane_b32 v254, s2, 2
	s_nop 1
	v_writelane_b32 v254, s3, 3
	s_and_b64 s[2:3], s[6:7], s[2:3]
	s_mov_b64 exec, s[2:3]
	s_cbranch_execz .LBB0_5
	s_mov_b64 s[8:9], exec
	v_mbcnt_lo_u32_b32 v1, s8, 0
	v_mbcnt_hi_u32_b32 v1, s9, v1
	v_cmp_eq_u32_e32 vcc, 0, v1
	s_and_b64 s[2:3], exec, vcc
	s_mov_b64 exec, s[2:3]
	s_cbranch_execz .LBB0_5
	s_lshl_b32 s2, s33, 8
	s_bcnt1_i32_b64 s3, s[8:9]
	v_mov_b32_e32 v1, s2
	v_mov_b32_e32 v2, s3
	global_atomic_add v1, v2, s[62:63] offset:1024
